# code placement: K-loop heads at a 64-byte boundary + 4 bytes (other instruction phase)
# baseline (speedup 1.0000x reference)
; DI void zero_acc(f32x4 (&acc)[4][4]) {
; #pragma unroll
;     for (int i = 0; i < 4; ++i)
; #pragma unroll
;         for (int j = 0; j < 4; ++j) acc[i][j] = (f32x4){0.f, 0.f, 0.f, 0.f};
; }
; DI void gemm_gu(const Params& p, size_t woff, int bid, int nb, char* smem, const int tid) {
;     ...
;     for (; have; tm = tm2, tn = tn2) {
;         have = ti.next(tm2, tn2);
;         const int m0 = tm * 256, n0 = tn * 128;
;         f32x4 acc[4][4]; zero_acc(acc);
;         gemm_stream(A, 1024, Bt, 1024, 1024, m0, n0, have, tm2 * 256, tn2 * 128, smem, acc, tid, rg);
.Lgu_nonext:
	v_mov_b64_e32 v[24:25], 0
	v_mov_b64_e32 v[26:27], 0
	v_mov_b64_e32 v[28:29], 0
	v_mov_b64_e32 v[30:31], 0
	v_mov_b64_e32 v[32:33], 0
	v_mov_b64_e32 v[34:35], 0
	v_mov_b64_e32 v[36:37], 0
	v_mov_b64_e32 v[38:39], 0
	v_mov_b64_e32 v[40:41], 0
	v_mov_b64_e32 v[42:43], 0
	v_mov_b64_e32 v[44:45], 0
	v_mov_b64_e32 v[46:47], 0
	v_mov_b64_e32 v[48:49], 0
	v_mov_b64_e32 v[50:51], 0
	v_mov_b64_e32 v[52:53], 0
	v_mov_b64_e32 v[54:55], 0
	v_mov_b64_e32 v[56:57], 0
	v_mov_b64_e32 v[58:59], 0
	v_mov_b64_e32 v[60:61], 0
	v_mov_b64_e32 v[62:63], 0
	v_mov_b64_e32 v[64:65], 0
	v_mov_b64_e32 v[66:67], 0
	v_mov_b64_e32 v[68:69], 0
	v_mov_b64_e32 v[70:71], 0
	v_mov_b64_e32 v[72:73], 0
	v_mov_b64_e32 v[74:75], 0
	v_mov_b64_e32 v[76:77], 0
	v_mov_b64_e32 v[78:79], 0
	v_mov_b64_e32 v[80:81], 0
	v_mov_b64_e32 v[82:83], 0
	v_mov_b64_e32 v[84:85], 0
	v_mov_b64_e32 v[86:87], 0
	v_mov_b64_e32 v[88:89], 0
	v_mov_b64_e32 v[90:91], 0
	v_mov_b64_e32 v[92:93], 0
	v_mov_b64_e32 v[94:95], 0
	v_mov_b64_e32 v[96:97], 0
	v_mov_b64_e32 v[98:99], 0
	v_mov_b64_e32 v[100:101], 0
	v_mov_b64_e32 v[102:103], 0
	v_mov_b64_e32 v[104:105], 0
	v_mov_b64_e32 v[106:107], 0
	v_mov_b64_e32 v[108:109], 0
	v_mov_b64_e32 v[110:111], 0
	v_mov_b64_e32 v[112:113], 0
	v_mov_b64_e32 v[114:115], 0
	v_mov_b64_e32 v[116:117], 0
	v_mov_b64_e32 v[118:119], 0
	v_mov_b64_e32 v[120:121], 0
	v_mov_b64_e32 v[122:123], 0
	v_mov_b64_e32 v[124:125], 0
	v_mov_b64_e32 v[126:127], 0
	v_mov_b64_e32 v[128:129], 0
	v_mov_b64_e32 v[130:131], 0
	v_mov_b64_e32 v[132:133], 0
	v_mov_b64_e32 v[134:135], 0
	v_mov_b64_e32 v[136:137], 0
	v_mov_b64_e32 v[138:139], 0
	v_mov_b64_e32 v[140:141], 0
	v_mov_b64_e32 v[142:143], 0
	v_mov_b64_e32 v[144:145], 0
	v_mov_b64_e32 v[146:147], 0
	v_mov_b64_e32 v[148:149], 0
	v_mov_b64_e32 v[150:151], 0
	s_add_u32 s0, s54, 7
	.p2alignl 6, 3212836864
	s_nop 0

; DI void zero_acc(f32x4 (&acc)[4][4]) {
; #pragma unroll
;     for (int i = 0; i < 4; ++i)
; #pragma unroll
;         for (int j = 0; j < 4; ++j) acc[i][j] = (f32x4){0.f, 0.f, 0.f, 0.f};
; }
; DI void gemm_y(const Params& p, const bf16_t* A, int lda, size_t woff, int K, int kper, int bid, int nb, char* smem, const int tid) {
;     ...
;     for (; have; tm = tm2, tn = tn2) {
;         have = ti.next(tm2, tn2);
;         const int m0 = tm * 256, n0 = tn * 128;
;         f32x4 acc[4][4]; zero_acc(acc);
;         gemm_stream(A, lda, Bt, K, K, m0, n0, have, tm2 * 256, tn2 * 128, smem, acc, tid, rg);
;         epi_y<0>(p, acc, m0, n0, tid);
;     }
;     const int S = (K / 64) / kper;
;     for (int u = bid; u < 8 * S; u += nb) {
;         const int tile = u / S, part = u - tile * S, m0 = NP, n0 = tile * 128;
;         f32x4 acc[4][4]; zero_acc(acc);
;         gemm_mainloop(A + part * kper * 64, lda, Bt + part * kper * 64, K, kper * 64, m0, n0, smem, acc, tid);
.Lgyd_nx_done:
	v_mov_b64_e32 v[24:25], 0
	v_mov_b64_e32 v[26:27], 0
	v_mov_b64_e32 v[28:29], 0
	v_mov_b64_e32 v[30:31], 0
	v_mov_b64_e32 v[32:33], 0
	v_mov_b64_e32 v[34:35], 0
	v_mov_b64_e32 v[36:37], 0
	v_mov_b64_e32 v[38:39], 0
	v_mov_b64_e32 v[40:41], 0
	v_mov_b64_e32 v[42:43], 0
	v_mov_b64_e32 v[44:45], 0
	v_mov_b64_e32 v[46:47], 0
	v_mov_b64_e32 v[48:49], 0
	v_mov_b64_e32 v[50:51], 0
	v_mov_b64_e32 v[52:53], 0
	v_mov_b64_e32 v[54:55], 0
	v_mov_b64_e32 v[56:57], 0
	v_mov_b64_e32 v[58:59], 0
	v_mov_b64_e32 v[60:61], 0
	v_mov_b64_e32 v[62:63], 0
	v_mov_b64_e32 v[64:65], 0
	v_mov_b64_e32 v[66:67], 0
	v_mov_b64_e32 v[68:69], 0
	v_mov_b64_e32 v[70:71], 0
	v_mov_b64_e32 v[72:73], 0
	v_mov_b64_e32 v[74:75], 0
	v_mov_b64_e32 v[76:77], 0
	v_mov_b64_e32 v[78:79], 0
	v_mov_b64_e32 v[80:81], 0
	v_mov_b64_e32 v[82:83], 0
	v_mov_b64_e32 v[84:85], 0
	v_mov_b64_e32 v[86:87], 0
	v_mov_b64_e32 v[88:89], 0
	v_mov_b64_e32 v[90:91], 0
	v_mov_b64_e32 v[92:93], 0
	v_mov_b64_e32 v[94:95], 0
	v_mov_b64_e32 v[96:97], 0
	v_mov_b64_e32 v[98:99], 0
	v_mov_b64_e32 v[100:101], 0
	v_mov_b64_e32 v[102:103], 0
	v_mov_b64_e32 v[104:105], 0
	v_mov_b64_e32 v[106:107], 0
	v_mov_b64_e32 v[108:109], 0
	v_mov_b64_e32 v[110:111], 0
	v_mov_b64_e32 v[112:113], 0
	v_mov_b64_e32 v[114:115], 0
	v_mov_b64_e32 v[116:117], 0
	v_mov_b64_e32 v[118:119], 0
	v_mov_b64_e32 v[120:121], 0
	v_mov_b64_e32 v[122:123], 0
	v_mov_b64_e32 v[124:125], 0
	v_mov_b64_e32 v[126:127], 0
	v_mov_b64_e32 v[128:129], 0
	v_mov_b64_e32 v[130:131], 0
	v_mov_b64_e32 v[132:133], 0
	v_mov_b64_e32 v[134:135], 0
	v_mov_b64_e32 v[136:137], 0
	v_mov_b64_e32 v[138:139], 0
	v_mov_b64_e32 v[140:141], 0
	v_mov_b64_e32 v[142:143], 0
	v_mov_b64_e32 v[144:145], 0
	v_mov_b64_e32 v[146:147], 0
	v_mov_b64_e32 v[148:149], 0
	v_mov_b64_e32 v[150:151], 0
	s_cmp_eq_u32 s55, 0
	s_cselect_b32 s0, 21, 1
	s_add_u32 s0, s0, s54
	s_cmp_eq_u32 s0, 0
	s_cbranch_scc1 .Lgyd_kdone
	.p2alignl 6, 3212836864
	s_nop 0

; DI void zero_acc(f32x4 (&acc)[4][4]) {
; #pragma unroll
;     for (int i = 0; i < 4; ++i)
; #pragma unroll
;         for (int j = 0; j < 4; ++j) acc[i][j] = (f32x4){0.f, 0.f, 0.f, 0.f};
; }
; DI void gemm_y(const Params& p, const bf16_t* A, int lda, size_t woff, int K, int kper, int bid, int nb, char* smem, const int tid) {
;     ...
;     for (; have; tm = tm2, tn = tn2) {
;         have = ti.next(tm2, tn2);
;         const int m0 = tm * 256, n0 = tn * 128;
;         f32x4 acc[4][4]; zero_acc(acc);
;         gemm_stream(A, lda, Bt, K, K, m0, n0, have, tm2 * 256, tn2 * 128, smem, acc, tid, rg);
;         epi_y<0>(p, acc, m0, n0, tid);
;     }
;     const int S = (K / 64) / kper;
;     for (int u = bid; u < 8 * S; u += nb) {
;         const int tile = u / S, part = u - tile * S, m0 = NP, n0 = tile * 128;
;         f32x4 acc[4][4]; zero_acc(acc);
;         gemm_mainloop(A + part * kper * 64, lda, Bt + part * kper * 64, K, kper * 64, m0, n0, smem, acc, tid);
.Lgyo_nx_done:
	v_mov_b64_e32 v[24:25], 0
	v_mov_b64_e32 v[26:27], 0
	v_mov_b64_e32 v[28:29], 0
	v_mov_b64_e32 v[30:31], 0
	v_mov_b64_e32 v[32:33], 0
	v_mov_b64_e32 v[34:35], 0
	v_mov_b64_e32 v[36:37], 0
	v_mov_b64_e32 v[38:39], 0
	v_mov_b64_e32 v[40:41], 0
	v_mov_b64_e32 v[42:43], 0
	v_mov_b64_e32 v[44:45], 0
	v_mov_b64_e32 v[46:47], 0
	v_mov_b64_e32 v[48:49], 0
	v_mov_b64_e32 v[50:51], 0
	v_mov_b64_e32 v[52:53], 0
	v_mov_b64_e32 v[54:55], 0
	v_mov_b64_e32 v[56:57], 0
	v_mov_b64_e32 v[58:59], 0
	v_mov_b64_e32 v[60:61], 0
	v_mov_b64_e32 v[62:63], 0
	v_mov_b64_e32 v[64:65], 0
	v_mov_b64_e32 v[66:67], 0
	v_mov_b64_e32 v[68:69], 0
	v_mov_b64_e32 v[70:71], 0
	v_mov_b64_e32 v[72:73], 0
	v_mov_b64_e32 v[74:75], 0
	v_mov_b64_e32 v[76:77], 0
	v_mov_b64_e32 v[78:79], 0
	v_mov_b64_e32 v[80:81], 0
	v_mov_b64_e32 v[82:83], 0
	v_mov_b64_e32 v[84:85], 0
	v_mov_b64_e32 v[86:87], 0
	v_mov_b64_e32 v[88:89], 0
	v_mov_b64_e32 v[90:91], 0
	v_mov_b64_e32 v[92:93], 0
	v_mov_b64_e32 v[94:95], 0
	v_mov_b64_e32 v[96:97], 0
	v_mov_b64_e32 v[98:99], 0
	v_mov_b64_e32 v[100:101], 0
	v_mov_b64_e32 v[102:103], 0
	v_mov_b64_e32 v[104:105], 0
	v_mov_b64_e32 v[106:107], 0
	v_mov_b64_e32 v[108:109], 0
	v_mov_b64_e32 v[110:111], 0
	v_mov_b64_e32 v[112:113], 0
	v_mov_b64_e32 v[114:115], 0
	v_mov_b64_e32 v[116:117], 0
	v_mov_b64_e32 v[118:119], 0
	v_mov_b64_e32 v[120:121], 0
	v_mov_b64_e32 v[122:123], 0
	v_mov_b64_e32 v[124:125], 0
	v_mov_b64_e32 v[126:127], 0
	v_mov_b64_e32 v[128:129], 0
	v_mov_b64_e32 v[130:131], 0
	v_mov_b64_e32 v[132:133], 0
	v_mov_b64_e32 v[134:135], 0
	v_mov_b64_e32 v[136:137], 0
	v_mov_b64_e32 v[138:139], 0
	v_mov_b64_e32 v[140:141], 0
	v_mov_b64_e32 v[142:143], 0
	v_mov_b64_e32 v[144:145], 0
	v_mov_b64_e32 v[146:147], 0
	v_mov_b64_e32 v[148:149], 0
	v_mov_b64_e32 v[150:151], 0
	s_cmp_eq_u32 s55, 0
	s_cselect_b32 s0, 7, 0
	s_add_u32 s0, s0, s54
	s_cmp_eq_u32 s0, 0
	s_cbranch_scc1 .Lgyo_kdone
	.p2alignl 6, 3212836864
	s_nop 0
